# split packed f32 VALU (v_pk_add/v_pk_fma) beside MFMAs into scalar ops in MLA loop and diff-attn producer softmax; MLA run-prologue vmcnt(0) relaxed to lgkmcnt(0); on top of MLA loop rewrite + diff pr
# speedup vs baseline: 1.0066x; 1.0066x over previous
; __device__ __forceinline__ unsigned cvtpk(float lo, float hi) { unsigned r; asm volatile("v_cvt_pk_bf16_f32 %0, %1, %2" : "=v"(r) : "v"(lo), "v"(hi)); return r; }
; __device__ __forceinline__ float exp_sum32(f32x16& p0, f32x16& p1, float c1, float nm) {
;     ...
;     for (int r = 0; r < 16; r += 2) {
;         f32x2 a = (f32x2){p0[r], p0[r + 1]} * c1 + nm, b = (f32x2){p1[r], p1[r + 1]} * c1 + nm;
;         a.x = __builtin_amdgcn_exp2f(a.x); a.y = __builtin_amdgcn_exp2f(a.y); b.x = __builtin_amdgcn_exp2f(b.x); b.y = __builtin_amdgcn_exp2f(b.y);
;         p0[r] = a.x; p0[r + 1] = a.y; p1[r] = b.x; p1[r + 1] = b.y; acc += a; acc += b;
; __device__ __forceinline__ float attn_diff_pair(ALAS unsigned char* lds, const Args& A, int q0, f32x16 (&o)[4]) {
;     ...
;                 const float nm = -mrun * A.c1;
;                 lrun += exp_sum32(s0, s1, A.c1, nm);
;                 { u32x4 w;
;                   w.x = cvtpk(s0[0], s0[1]); w.y = cvtpk(s0[2], s0[3]); w.z = cvtpk(s0[4], s0[5]); w.w = cvtpk(s0[6], s0[7]); pa[0] = __builtin_bit_cast(bf16x8, w);
;                   w.x = cvtpk(s0[8], s0[9]); w.y = cvtpk(s0[10], s0[11]); w.z = cvtpk(s0[12], s0[13]); w.w = cvtpk(s0[14], s0[15]); pa[1] = __builtin_bit_cast(bf16x8, w);
;                   w.x = cvtpk(s1[0], s1[1]); w.y = cvtpk(s1[2], s1[3]); w.z = cvtpk(s1[4], s1[5]); w.w = cvtpk(s1[6], s1[7]); pa[2] = __builtin_bit_cast(bf16x8, w);
;                   w.x = cvtpk(s1[8], s1[9]); w.y = cvtpk(s1[10], s1[11]); w.z = cvtpk(s1[12], s1[13]); w.w = cvtpk(s1[14], s1[15]); pa[3] = __builtin_bit_cast(bf16x8, w); }
;                 if (actp) { while (*flagp != (unsigned)it) __builtin_amdgcn_s_sleep(1); }
.LBB0_400:
	v_mul_f32_e32 v110, 0xbe0293ee, v251
	v_fma_f32 v14, v14, s80, v110
	v_fma_f32 v15, v15, s80, v110
	v_fma_f32 v10, v10, s80, v110
	v_fma_f32 v11, v11, s80, v110
	v_fma_f32 v8, v8, s80, v110
	v_fma_f32 v9, v9, s80, v110
	v_fma_f32 v6, v6, s80, v110
	v_fma_f32 v7, v7, s80, v110
	v_fma_f32 v4, v4, s80, v110
	v_fma_f32 v5, v5, s80, v110
	v_fma_f32 v112, v112, s80, v110
	v_fma_f32 v113, v113, s80, v110
	v_fma_f32 v96, v96, s80, v110
	v_fma_f32 v97, v97, s80, v110
	v_fma_f32 v114, v114, s80, v110
	v_fma_f32 v115, v115, s80, v110
	v_fma_f32 v98, v98, s80, v110
	v_fma_f32 v99, v99, s80, v110
	v_fma_f32 v100, v100, s80, v110
	v_fma_f32 v101, v101, s80, v110
	v_exp_f32_e32 v116, v14
	v_exp_f32_e32 v117, v15
	v_fma_f32 v14, v102, s80, v110
	v_fma_f32 v15, v103, s80, v110
	v_exp_f32_e32 v118, v10
	v_exp_f32_e32 v119, v11
	v_fma_f32 v10, v104, s80, v110
	v_fma_f32 v11, v105, s80, v110
	v_exp_f32_e32 v120, v8
	v_exp_f32_e32 v121, v9
	v_fma_f32 v8, v106, s80, v110
	v_fma_f32 v9, v107, s80, v110
	v_exp_f32_e32 v122, v6
	v_exp_f32_e32 v123, v7
	v_fma_f32 v6, v108, s80, v110
	v_fma_f32 v7, v109, s80, v110
	v_exp_f32_e32 v124, v4
	v_exp_f32_e32 v125, v5
	v_fma_f32 v2, v2, s80, v110
	v_fma_f32 v3, v3, s80, v110
	v_fma_f32 v4, v12, s80, v110
	v_fma_f32 v5, v13, s80, v110
	v_exp_f32_e32 v112, v112
	v_exp_f32_e32 v113, v113
	v_exp_f32_e32 v96, v96
	v_exp_f32_e32 v97, v97
	v_exp_f32_e32 v114, v114
	v_exp_f32_e32 v115, v115
	v_exp_f32_e32 v98, v98
	v_exp_f32_e32 v99, v99
	v_exp_f32_e32 v100, v100
	v_exp_f32_e32 v101, v101
	v_exp_f32_e32 v102, v14
	v_exp_f32_e32 v103, v15
	v_exp_f32_e32 v104, v10
	v_exp_f32_e32 v105, v11
	v_exp_f32_e32 v106, v8
	v_exp_f32_e32 v107, v9
	v_exp_f32_e32 v108, v6
	v_exp_f32_e32 v109, v7
	v_exp_f32_e32 v126, v2
	v_exp_f32_e32 v127, v3
	v_exp_f32_e32 v110, v4
	v_exp_f32_e32 v111, v5
	s_and_b64 vcc, exec, s[18:19]
	v_cvt_pk_bf16_f32 v204, v112, v113
	v_cvt_pk_bf16_f32 v205, v114, v115
	v_cvt_pk_bf16_f32 v206, v116, v117
	v_cvt_pk_bf16_f32 v207, v118, v119
	v_cvt_pk_bf16_f32 v200, v120, v121
	v_cvt_pk_bf16_f32 v201, v122, v123
	v_cvt_pk_bf16_f32 v202, v124, v125
	v_cvt_pk_bf16_f32 v203, v126, v127
	v_cvt_pk_bf16_f32 v196, v96, v97
	v_cvt_pk_bf16_f32 v197, v98, v99
	v_cvt_pk_bf16_f32 v198, v100, v101
	v_cvt_pk_bf16_f32 v199, v102, v103
	v_cvt_pk_bf16_f32 v192, v104, v105
	v_cvt_pk_bf16_f32 v193, v106, v107
	v_cvt_pk_bf16_f32 v194, v108, v109
	v_cvt_pk_bf16_f32 v195, v110, v111
	s_cbranch_vccnz .LBB0_403
	v_mov_b32_e32 v2, s47
	ds_read_b32 v2, v2
	s_waitcnt lgkmcnt(0)
	v_cmp_eq_u32_e32 vcc, s95, v2
	s_cbranch_vccnz .LBB0_403

; #define ALAS __attribute__((address_space(3)))
; __device__ __forceinline__ float exp_sum32(f32x16& p0, f32x16& p1, float c1, float nm) {
;     ...
;         p0[r] = a.x; p0[r + 1] = a.y; p1[r] = b.x; p1[r + 1] = b.y; acc += a; acc += b;
;     }
;     return acc.x + acc.y;
; __device__ __forceinline__ float attn_diff_pair(ALAS unsigned char* lds, const Args& A, int q0, f32x16 (&o)[4]) {
;     ...
;                 if (actp) { while (*flagp != (unsigned)it) __builtin_amdgcn_s_sleep(1); }
;                 asm volatile("" ::: "memory");
; #pragma unroll
;                 for (int ks = 0; ks < 4; ++ks) *(ALAS bf16x8*)(pslot + ks * 1024) = pa[ks];
;                 *aslot = alpha;
.LBB0_403:
	v_add_f32_e32 v2, 0, v112
	v_add_f32_e32 v3, 0, v113
	s_nop 0
	v_add_f32_e32 v2, v96, v2
	v_add_f32_e32 v3, v97, v3
	s_nop 0
	v_add_f32_e32 v2, v114, v2
	v_add_f32_e32 v3, v115, v3
	s_nop 0
	v_add_f32_e32 v2, v98, v2
	v_add_f32_e32 v3, v99, v3
	s_nop 0
	v_add_f32_e32 v2, v116, v2
	v_add_f32_e32 v3, v117, v3
	s_nop 0
	v_add_f32_e32 v2, v100, v2
	v_add_f32_e32 v3, v101, v3
	s_nop 0
	v_add_f32_e32 v2, v118, v2
	v_add_f32_e32 v3, v119, v3
	s_nop 0
	v_add_f32_e32 v2, v102, v2
	v_add_f32_e32 v3, v103, v3
	s_nop 0
	v_add_f32_e32 v2, v120, v2
	v_add_f32_e32 v3, v121, v3
	s_nop 0
	v_add_f32_e32 v2, v104, v2
	v_add_f32_e32 v3, v105, v3
	s_nop 0
	v_add_f32_e32 v2, v122, v2
	v_add_f32_e32 v3, v123, v3
	s_nop 0
	v_add_f32_e32 v2, v106, v2
	v_add_f32_e32 v3, v107, v3
	s_nop 0
	v_add_f32_e32 v2, v124, v2
	v_add_f32_e32 v3, v125, v3
	s_nop 0
	v_add_f32_e32 v2, v108, v2
	v_add_f32_e32 v3, v109, v3
	s_nop 0
	v_add_f32_e32 v2, v126, v2
	v_add_f32_e32 v3, v127, v3
	s_nop 0
	v_add_f32_e32 v2, v110, v2
	v_add_f32_e32 v3, v111, v3
	s_nop 0
	v_add_f32_e32 v2, v2, v3
	v_add_f32_e32 v250, v250, v2
	v_add_u32_e32 v2, s0, v242
	ds_write_b128 v2, v[204:207]
	ds_write_b128 v2, v[200:203] offset:1024
	ds_write_b128 v2, v[196:199] offset:2048
	ds_write_b128 v2, v[192:195] offset:3072
	v_add_u32_e32 v2, s46, v235
	ds_write_b32 v2, v0
	s_andn2_b64 vcc, exec, s[88:89]
	s_cbranch_vccnz .LBB0_382

; #define ALAS __attribute__((address_space(3)))
; __device__ __forceinline__ float attn_mla_lag(ALAS unsigned char* lds, const Args& A, int q0, f32x16 (&o)[4]) {
;     ...
;     auto issueK = [&](int t) {
;         const unsigned dst = (unsigned)__builtin_amdgcn_readfirstlane((int)(unsigned)(uintptr_t)(lds + KOFF + (t & 1) * KBYTES + wid * 1024));
;         const char* kb0 = (const char*)(A.K + (size_t)t * 64 * A.kpitch) + kofs;
;         glds16(kb0, dst); glds16(kb0 + 128, dst + 8192);
;         glds16((const char*)(A.K2 + (size_t)t * 64 * A.k2pitch) + k2ofs, dst + 16384);
;     };
;     auto issueV = [&](int t) {
;         const unsigned dst = (unsigned)__builtin_amdgcn_readfirstlane((int)(unsigned)(uintptr_t)(lds + VOFF + (t & 1) * VBYTES + wid * 1024));
;         const char* vb0 = (const char*)(A.V + (size_t)t * 64 * A.vpitch) + vofs;
;         glds16(vb0, dst); glds16(vb0 + (size_t)32 * A.vpitch * 2, dst + 8192);
;     };
; #pragma unroll
;     for (int db = 0; db < NDB; ++db)
; #pragma unroll
;         for (int r = 0; r < 16; ++r) o[db][r] = 0.f;
;     float mrun = -1.0e30f, lrun = 0.f;
;     bf16x8 pa[4];
; #pragma unroll
;     for (int i = 0; i < 4; ++i) pa[i] = (bf16x8){0, 0, 0, 0, 0, 0, 0, 0};
;     const int koff = r32 * 128, kx = (r32 >> 1) & 7;
;     const int voff = (4 * hi + ((lane & 15) >> 2)) * 64 + ((lane >> 4) & 1) * 32 + (lane & 3) * 8;
;     f32x16 s0, s1;
;     auto qk = [&](int t) {
;         const ALAS unsigned char* kbuf = lds + KOFF + (t & 1) * KBYTES;
;         const f32x16 z = {0.f, 0.f, 0.f, 0.f, 0.f, 0.f, 0.f, 0.f, 0.f, 0.f, 0.f, 0.f, 0.f, 0.f, 0.f, 0.f};
; #pragma unroll
;         for (int s = 0; s < NSTEP; ++s) {
;             const int kb = s >> 2, ch = 2 * (s & 3) + hi;
;             const ALAS unsigned char* p = kbuf + kb * 8192 + koff + ((ch ^ kx) * 16);
;             const bf16x8 k0 = *(const ALAS bf16x8*)p, k1 = *(const ALAS bf16x8*)(p + 4096);
;             s0 = __builtin_amdgcn_mfma_f32_32x32x16_bf16(k0, qr[s], s == 0 ? z : s0, 0, 0, 0);
;             s1 = __builtin_amdgcn_mfma_f32_32x32x16_bf16(k1, qr[s], s == 0 ? z : s1, 0, 0, 0);
;         }
;         asm volatile("s_nop 15\n\ts_nop 7" : "+v"(s0), "+v"(s1));
.LBB0_1086:
	s_lshl_b32 s0, s0, 10
	s_add_i32 s88, s0, 0
	s_mov_b32 s0, m0
	s_mov_b32 m0, s88
	s_nop 0
	global_load_lds_dwordx4 v[188:189], off
	s_mov_b32 m0, s0
	s_add_i32 s0, s88, 0x2000
	s_mov_b32 s1, m0
	s_mov_b32 m0, s0
	s_nop 0
	global_load_lds_dwordx4 v[190:191], off
	s_mov_b32 m0, s1
	s_add_i32 s0, s88, 0x4000
	s_mov_b32 s1, m0
	s_mov_b32 m0, s0
	s_nop 0
	global_load_lds_dwordx4 v[170:171], off
	s_mov_b32 m0, s1
	s_waitcnt vmcnt(0)
	s_barrier
	s_add_i32 s0, s88, 0x6000
	s_mov_b32 s1, m0
	s_mov_b32 m0, s0
	s_nop 0
	global_load_lds_dwordx4 v[192:193], off
	s_mov_b32 m0, s1
	s_add_i32 s1, s0, 0x2000
	s_mov_b32 s4, m0
	s_mov_b32 m0, s1
	s_nop 0
	global_load_lds_dwordx4 v[194:195], off
	s_mov_b32 m0, s4
	s_addk_i32 s0, 0x4000
	s_mov_b32 s1, m0
	s_mov_b32 m0, s0
	s_nop 0
	global_load_lds_dwordx4 v[172:173], off
	s_mov_b32 m0, s1
	s_add_i32 s0, s88, 0xc000
	s_mov_b32 s1, m0
	s_mov_b32 m0, s0
	s_nop 0
	global_load_lds_dwordx4 v[196:197], off
	s_mov_b32 m0, s1
	s_addk_i32 s0, 0x2000
	s_mov_b32 s1, m0
	s_mov_b32 m0, s0
	s_nop 0
	global_load_lds_dwordx4 v[198:199], off
	s_mov_b32 m0, s1
	v_add_u32_e32 v0, v218, v219
	ds_read_b128 v[2:5], v0
	ds_read_b128 v[6:9], v0 offset:4096
	s_waitcnt lgkmcnt(0)
	v_mfma_f32_32x32x16_bf16 v[50:65], v[2:5], v[98:101], 0
	v_add_u32_e32 v10, v218, v220
	v_add_u32_e32 v11, v218, v221
	v_add_u32_e32 v12, v218, v222
	s_cmp_gt_u32 s77, 62
	v_mfma_f32_32x32x16_bf16 v[34:49], v[6:9], v[98:101], 0
	ds_read_b128 v[2:5], v10
	ds_read_b128 v[6:9], v10 offset:4096
	s_waitcnt lgkmcnt(1)
	v_mfma_f32_32x32x16_bf16 v[50:65], v[2:5], v[102:105], v[50:65]
	s_waitcnt lgkmcnt(0)
	v_mfma_f32_32x32x16_bf16 v[34:49], v[6:9], v[102:105], v[34:49]
	ds_read_b128 v[2:5], v11
	ds_read_b128 v[6:9], v11 offset:4096
	s_waitcnt lgkmcnt(1)
	v_mfma_f32_32x32x16_bf16 v[50:65], v[2:5], v[106:109], v[50:65]
	s_waitcnt lgkmcnt(0)
	v_mfma_f32_32x32x16_bf16 v[34:49], v[6:9], v[106:109], v[34:49]
	ds_read_b128 v[2:5], v12
	ds_read_b128 v[6:9], v12 offset:4096
	s_waitcnt lgkmcnt(1)
	v_mfma_f32_32x32x16_bf16 v[50:65], v[2:5], v[110:113], v[50:65]
	s_waitcnt lgkmcnt(0)
	v_mfma_f32_32x32x16_bf16 v[34:49], v[6:9], v[110:113], v[34:49]
	ds_read_b128 v[2:5], v0 offset:8192
	ds_read_b128 v[6:9], v0 offset:12288
	s_waitcnt lgkmcnt(1)
	v_mfma_f32_32x32x16_bf16 v[50:65], v[2:5], v[114:117], v[50:65]
	s_waitcnt lgkmcnt(0)
	v_mfma_f32_32x32x16_bf16 v[34:49], v[6:9], v[114:117], v[34:49]
	ds_read_b128 v[2:5], v10 offset:8192
	ds_read_b128 v[6:9], v10 offset:12288
	s_waitcnt lgkmcnt(1)
	v_mfma_f32_32x32x16_bf16 v[50:65], v[2:5], v[118:121], v[50:65]
	s_waitcnt lgkmcnt(0)
	v_mfma_f32_32x32x16_bf16 v[34:49], v[6:9], v[118:121], v[34:49]
	ds_read_b128 v[2:5], v11 offset:8192
	ds_read_b128 v[6:9], v11 offset:12288
	s_waitcnt lgkmcnt(1)
	v_mfma_f32_32x32x16_bf16 v[50:65], v[2:5], v[122:125], v[50:65]
	s_waitcnt lgkmcnt(0)
	v_mfma_f32_32x32x16_bf16 v[34:49], v[6:9], v[122:125], v[34:49]
	ds_read_b128 v[2:5], v12 offset:8192
	ds_read_b128 v[6:9], v12 offset:12288
	s_waitcnt lgkmcnt(1)
	v_mfma_f32_32x32x16_bf16 v[50:65], v[2:5], v[126:129], v[50:65]
	s_waitcnt lgkmcnt(0)
	v_mfma_f32_32x32x16_bf16 v[34:49], v[6:9], v[126:129], v[34:49]
	ds_read_b128 v[2:5], v0 offset:16384
	ds_read_b128 v[6:9], v0 offset:20480
	s_waitcnt lgkmcnt(1)
	v_mfma_f32_32x32x16_bf16 v[50:65], v[2:5], v[130:133], v[50:65]
	s_waitcnt lgkmcnt(0)
	v_mfma_f32_32x32x16_bf16 v[34:49], v[6:9], v[130:133], v[34:49]
	ds_read_b128 v[2:5], v10 offset:16384
	ds_read_b128 v[6:9], v10 offset:20480
	s_waitcnt lgkmcnt(1)
	v_mfma_f32_32x32x16_bf16 v[50:65], v[2:5], v[134:137], v[50:65]
	s_waitcnt lgkmcnt(0)
	v_mfma_f32_32x32x16_bf16 v[34:49], v[6:9], v[134:137], v[34:49]
	ds_read_b128 v[2:5], v11 offset:16384
	ds_read_b128 v[6:9], v11 offset:20480
	s_waitcnt lgkmcnt(1)
	v_mfma_f32_32x32x16_bf16 v[50:65], v[2:5], v[138:141], v[50:65]
	s_waitcnt lgkmcnt(0)
	v_mfma_f32_32x32x16_bf16 v[34:49], v[6:9], v[138:141], v[34:49]
	ds_read_b128 v[2:5], v12 offset:16384
	ds_read_b128 v[6:9], v12 offset:20480
	s_waitcnt lgkmcnt(1)
	v_mfma_f32_32x32x16_bf16 v[50:65], v[2:5], v[142:145], v[50:65]
	s_waitcnt lgkmcnt(0)
	v_mfma_f32_32x32x16_bf16 v[34:49], v[6:9], v[142:145], v[34:49]
	s_nop 15
	s_nop 7
	s_cbranch_scc1 .LBB0_1090
; __device__ __forceinline__ int crow(int r, int hi) { return (r & 3) + 8 * (r >> 2) + 4 * hi; }
; __device__ __forceinline__ float attn_mla_lag(ALAS unsigned char* lds, const Args& A, int q0, f32x16 (&o)[4]) {
;     ...
;         if (act) {
;             if (64 * t + 63 > qrow0) {
; #pragma unroll
;                 for (int r = 0; r < 16; ++r) { const int kv = 64 * t + crow(r, hi); if (kv > qidx) s0[r] = -INFINITY; if (kv + 32 > qidx) s1[r] = -INFINITY; }
;             }
	v_or_b32_e32 v0, 32, v223
	v_cmp_le_u32_e64 s[4:5], v0, v242
	v_or_b32_e32 v0, 33, v223
	v_cmp_le_u32_e64 s[6:7], v0, v242
	v_or_b32_e32 v0, 2, v223
	v_cmp_le_u32_e64 s[24:25], v225, v242
	s_nop 4
	v_cndmask_b32_e64 v35, v239, v35, s[6:7]
	v_cmp_le_u32_e64 s[6:7], v0, v242
	v_or_b32_e32 v0, 34, v223
	v_cmp_le_u32_e64 s[8:9], v0, v242
	v_or_b32_e32 v0, 3, v223
	v_cmp_le_u32_e64 s[26:27], v227, v242
	v_cndmask_b32_e64 v36, v239, v36, s[8:9]
	v_cmp_le_u32_e64 s[8:9], v0, v242
	v_or_b32_e32 v0, 35, v223
	v_cmp_le_u32_e64 s[10:11], v0, v242
	v_or_b32_e32 v0, 8, v223
	v_cmp_le_u32_e64 s[28:29], v229, v242
	v_cndmask_b32_e64 v37, v239, v37, s[10:11]
	v_cmp_le_u32_e64 s[10:11], v0, v242
	v_or_b32_e32 v0, 40, v223
	v_cmp_le_u32_e64 s[12:13], v0, v242
	v_or_b32_e32 v0, 9, v223
	v_cmp_le_u32_e64 s[30:31], v231, v242
	v_cndmask_b32_e64 v38, v239, v38, s[12:13]
	v_cmp_le_u32_e64 s[12:13], v0, v242
	v_or_b32_e32 v0, 41, v223
	v_cmp_le_u32_e64 s[14:15], v0, v242
	v_or_b32_e32 v0, 10, v223
	v_cmp_le_u32_e64 s[34:35], v235, v242
	v_cndmask_b32_e64 v39, v239, v39, s[14:15]
	v_cmp_le_u32_e64 s[14:15], v0, v242
	v_or_b32_e32 v0, 42, v223
	v_cmp_le_u32_e64 s[16:17], v0, v242
	v_or_b32_e32 v0, 11, v223
	v_cmp_le_u32_e32 vcc, v223, v242
	v_cndmask_b32_e64 v40, v239, v40, s[16:17]
	v_cmp_le_u32_e64 s[16:17], v0, v242
	v_or_b32_e32 v0, 43, v223
	v_cmp_le_u32_e64 s[18:19], v0, v242
	v_or_b32_e32 v0, 16, v223
	v_cndmask_b32_e64 v34, v239, v34, s[4:5]
	v_cndmask_b32_e64 v41, v239, v41, s[18:19]
	v_cmp_le_u32_e64 s[18:19], v0, v242
	v_or_b32_e32 v0, 48, v223
	v_cmp_le_u32_e64 s[20:21], v0, v242
	v_or_b32_e32 v0, 17, v223
	v_cmp_lt_u32_e64 s[4:5], v223, v242
	v_cndmask_b32_e64 v42, v239, v42, s[20:21]
	v_cmp_le_u32_e64 s[20:21], v0, v242
	v_or_b32_e32 v0, 49, v223
	v_cmp_le_u32_e64 s[22:23], v0, v242
	v_cndmask_b32_e64 v44, v239, v44, s[24:25]
	v_cmp_le_u32_e64 s[24:25], v226, v242
	v_cndmask_b32_e64 v43, v239, v43, s[22:23]
	v_cmp_le_u32_e64 s[22:23], v224, v242
	v_cndmask_b32_e64 v45, v239, v45, s[26:27]
	v_cmp_le_u32_e64 s[26:27], v228, v242
	v_cndmask_b32_e64 v46, v239, v46, s[28:29]
	v_cmp_le_u32_e64 s[28:29], v230, v242
	v_cndmask_b32_e64 v47, v239, v47, s[30:31]
	v_cmp_le_u32_e64 s[30:31], v234, v242
	v_cndmask_b32_e64 v48, v239, v48, s[34:35]
	v_cmp_le_u32_e64 s[34:35], v236, v242
	v_cmp_gt_u32_e64 s[38:39], v237, v242
	s_and_saveexec_b64 s[82:83], s[38:39]
	v_mov_b32_e32 v49, s43
	s_or_b64 exec, exec, s[82:83]
	v_cndmask_b32_e64 v51, v239, v51, s[4:5]
	v_cndmask_b32_e32 v50, v239, v50, vcc
	v_cndmask_b32_e64 v52, v239, v52, s[6:7]
	v_cndmask_b32_e64 v53, v239, v53, s[8:9]
	v_cndmask_b32_e64 v54, v239, v54, s[10:11]
	v_cndmask_b32_e64 v55, v239, v55, s[12:13]
	v_cndmask_b32_e64 v56, v239, v56, s[14:15]
	v_cndmask_b32_e64 v57, v239, v57, s[16:17]
	v_cndmask_b32_e64 v58, v239, v58, s[18:19]
	v_cndmask_b32_e64 v59, v239, v59, s[20:21]
	v_cndmask_b32_e64 v60, v239, v60, s[22:23]
	v_cndmask_b32_e64 v61, v239, v61, s[24:25]
	v_cndmask_b32_e64 v62, v239, v62, s[26:27]
	v_cndmask_b32_e64 v63, v239, v63, s[28:29]
	v_cndmask_b32_e64 v64, v239, v64, s[30:31]
	v_cndmask_b32_e64 v65, v239, v65, s[34:35]

; #define ALAS __attribute__((address_space(3)))
; __device__ __forceinline__ float max3f(float a, float b, float c) { float r; asm("v_max3_f32 %0, %1, %2, %3" : "=v"(r) : "v"(a), "v"(b), "v"(c)); return r; }
; #define MLA_LD(i, LO, HH) do { if ((i) < 16) { const int ks_ = (i) >> 2, db_ = (i) & 3; const ALAS unsigned char* vp_ = vbuf + ((2 * ks_) * NDB + db_) * 512 + voff; LO = vtr(vp_); HH = vtr(vp_ + NDB * 512); } } while (0)
; #define MLA_PVM(i) do { if ((i) & 1) { MLA_LD((i) + 1, vl0, vh0); MLA_MM(i, vl1, vh1); } else { MLA_LD((i) + 1, vl1, vh1); MLA_MM(i, vl0, vh0); } } while (0)
; #define MLA_F() __builtin_amdgcn_sched_barrier(0)
; __device__ __forceinline__ float attn_mla_lag(ALAS unsigned char* lds, const Args& A, int q0, f32x16 (&o)[4]) {
;     ...
;     for (int t = 1; t < ta; ++t) {
;         top(t);
;         qk(t);
;         float alpha;
;         {
;             const ALAS unsigned char* vbuf = lds + VOFF + ((t - 1) & 1) * VBYTES;
;             s16x4 vl0, vh0, vl1, vh1;
;     ...
;             float ma, mb;
;             MLA_LD(0, vl0, vh0);
;             MLA_PVM(0); ma = max3f(s0[0], s0[1], s1[0]); mb = max3f(s0[2], s0[3], s1[1]); ma = max3f(ma, s1[2], s1[3]); ma = max3f(ma, s0[4], s0[5]); mb = max3f(mb, s0[6], s0[7]); ma = max3f(ma, s1[4], s1[5]); MLA_F();
;             MLA_PVM(1); mb = max3f(mb, s1[6], s1[7]); ma = max3f(ma, s0[8], s0[9]); mb = max3f(mb, s0[10], s0[11]); ma = max3f(ma, s1[8], s1[9]); mb = max3f(mb, s1[10], s1[11]); ma = max3f(ma, s0[12], s0[13]); MLA_F();
;             MLA_PVM(2); mb = max3f(mb, s0[14], s0[15]); ma = max3f(ma, s1[12], s1[13]); mb = max3f(mb, s1[14], s1[15]); float mx = max3f(ma, mb, mb); MLA_F();
;             MLA_PVM(3);
.LBB0_1095:
	s_waitcnt vmcnt(0)
	s_barrier
	s_add_i32 s6, s8, 1
	s_bitcmp1_b32 s8, 0
	s_cselect_b32 s9, 0x6000, 0
	v_add_u32_e32 v0, s9, v218
	v_add_u32_e32 v245, v0, v219
	v_add_u32_e32 v254, v0, v220
	ds_read_b128 v[66:69], v245
	ds_read_b128 v[70:73], v245 offset:4096
	v_add_u32_e32 v233, v0, v221
	ds_read_b128 v[246:249], v254
	ds_read_b128 v[250:253], v254 offset:4096
	v_add_u32_e32 v0, v0, v222
	ds_read_b128 v[224:227], v233
	ds_read_b128 v[228:231], v233 offset:4096
	s_bitcmp1_b32 s6, 0
	s_cselect_b32 s7, 0x6000, 0
	s_add_i32 s7, s88, s7
	s_and_b32 s9, s5, 0x4000
	s_xor_b32 s10, s9, 0x4000
	v_add_u32_e32 v234, s10, v238
	s_add_i32 s9, s88, s9
	s_add_i32 s9, s9, 0xc000
	s_mov_b32 m0, s7
	s_waitcnt lgkmcnt(5)
	v_mfma_f32_32x32x16_bf16 v[82:97], v[66:69], v[98:101], 0
	s_waitcnt lgkmcnt(4)
	v_mfma_f32_32x32x16_bf16 v[66:81], v[70:73], v[98:101], 0
	s_waitcnt lgkmcnt(3)
	v_mfma_f32_32x32x16_bf16 v[82:97], v[246:249], v[102:105], v[82:97]
	s_waitcnt lgkmcnt(2)
	v_mfma_f32_32x32x16_bf16 v[66:81], v[250:253], v[102:105], v[66:81]
	ds_read_b128 v[246:249], v0
	ds_read_b128 v[250:253], v0 offset:4096
	global_load_lds_dwordx4 v[212:213], off
	s_add_i32 m0, s7, 0x2000
	v_lshl_add_u64 v[236:237], v[212:213], 0, s[68:69]
	s_waitcnt lgkmcnt(3)
	v_mfma_f32_32x32x16_bf16 v[82:97], v[224:227], v[106:109], v[82:97]
	s_waitcnt lgkmcnt(2)
	v_mfma_f32_32x32x16_bf16 v[66:81], v[228:231], v[106:109], v[66:81]
	ds_read_b128 v[224:227], v245 offset:8192
	ds_read_b128 v[228:231], v245 offset:12288
	s_waitcnt lgkmcnt(3)
	v_mfma_f32_32x32x16_bf16 v[82:97], v[246:249], v[110:113], v[82:97]
	s_waitcnt lgkmcnt(2)
	v_mfma_f32_32x32x16_bf16 v[66:81], v[250:253], v[110:113], v[66:81]
	ds_read_b128 v[246:249], v254 offset:8192
	ds_read_b128 v[250:253], v254 offset:12288
	global_load_lds_dwordx4 v[236:237], off
	s_add_i32 m0, s7, 0x4000
	s_waitcnt lgkmcnt(3)
	v_mfma_f32_32x32x16_bf16 v[82:97], v[224:227], v[114:117], v[82:97]
	s_waitcnt lgkmcnt(2)
	v_mfma_f32_32x32x16_bf16 v[66:81], v[228:231], v[114:117], v[66:81]
	ds_read_b128 v[224:227], v233 offset:8192
	ds_read_b128 v[228:231], v233 offset:12288
	s_waitcnt lgkmcnt(3)
	v_mfma_f32_32x32x16_bf16 v[82:97], v[246:249], v[118:121], v[82:97]
	s_waitcnt lgkmcnt(2)
	v_mfma_f32_32x32x16_bf16 v[66:81], v[250:253], v[118:121], v[66:81]
	ds_read_b128 v[246:249], v0 offset:8192
	ds_read_b128 v[250:253], v0 offset:12288
	global_load_lds_dwordx4 v[214:215], off
	s_mov_b32 m0, s9
	s_waitcnt lgkmcnt(3)
	v_mfma_f32_32x32x16_bf16 v[82:97], v[224:227], v[122:125], v[82:97]
	s_waitcnt lgkmcnt(2)
	v_mfma_f32_32x32x16_bf16 v[66:81], v[228:231], v[122:125], v[66:81]
	ds_read_b128 v[224:227], v245 offset:16384
	ds_read_b128 v[228:231], v245 offset:20480
	s_waitcnt lgkmcnt(3)
	v_mfma_f32_32x32x16_bf16 v[82:97], v[246:249], v[126:129], v[82:97]
	s_waitcnt lgkmcnt(2)
	v_mfma_f32_32x32x16_bf16 v[66:81], v[250:253], v[126:129], v[66:81]
	ds_read_b128 v[246:249], v254 offset:16384
	ds_read_b128 v[250:253], v254 offset:20480
	global_load_lds_dwordx4 v[216:217], off
	s_add_i32 m0, s9, 0x2000
	v_lshl_add_u64 v[236:237], v[216:217], 0, s[78:79]
	s_waitcnt lgkmcnt(3)
	v_mfma_f32_32x32x16_bf16 v[82:97], v[224:227], v[130:133], v[82:97]
	s_waitcnt lgkmcnt(2)
	v_mfma_f32_32x32x16_bf16 v[66:81], v[228:231], v[130:133], v[66:81]
	ds_read_b128 v[224:227], v233 offset:16384
	ds_read_b128 v[228:231], v233 offset:20480
	s_waitcnt lgkmcnt(3)
	v_mfma_f32_32x32x16_bf16 v[82:97], v[246:249], v[134:137], v[82:97]
	s_waitcnt lgkmcnt(2)
	v_mfma_f32_32x32x16_bf16 v[66:81], v[250:253], v[134:137], v[66:81]
	ds_read_b128 v[246:249], v0 offset:16384
	ds_read_b128 v[250:253], v0 offset:20480
	global_load_lds_dwordx4 v[236:237], off
	s_waitcnt lgkmcnt(3)
	v_mfma_f32_32x32x16_bf16 v[82:97], v[224:227], v[138:141], v[82:97]
	s_waitcnt lgkmcnt(2)
	v_mfma_f32_32x32x16_bf16 v[66:81], v[228:231], v[138:141], v[66:81]
	ds_read_b64_tr_b16 v[224:225], v234 offset:49152
	ds_read_b64_tr_b16 v[226:227], v234 offset:51200
	ds_read_b64_tr_b16 v[228:229], v234 offset:49664
	ds_read_b64_tr_b16 v[230:231], v234 offset:51712
	s_waitcnt lgkmcnt(5)
	v_mfma_f32_32x32x16_bf16 v[82:97], v[246:249], v[142:145], v[82:97]
	s_waitcnt lgkmcnt(4)
	v_mfma_f32_32x32x16_bf16 v[66:81], v[250:253], v[142:145], v[66:81]
	ds_read_b64_tr_b16 v[246:247], v234 offset:50176
	ds_read_b64_tr_b16 v[248:249], v234 offset:52224
	ds_read_b64_tr_b16 v[250:251], v234 offset:50688
	ds_read_b64_tr_b16 v[252:253], v234 offset:52736
	s_waitcnt lgkmcnt(6)
	v_mfma_f32_32x32x16_bf16 v[18:33], v[224:227], v[158:161], v[18:33]
	ds_read_b64_tr_b16 v[224:225], v234 offset:53248
	ds_read_b64_tr_b16 v[226:227], v234 offset:55296
	s_nop 1
	s_waitcnt lgkmcnt(6)
	v_mfma_f32_32x32x16_bf16 v[50:65], v[228:231], v[158:161], v[50:65]
	ds_read_b64_tr_b16 v[228:229], v234 offset:53760
	ds_read_b64_tr_b16 v[230:231], v234 offset:55808
	v_max3_f32 v0, v82, v83, v66
	v_max3_f32 v245, v84, v85, v67
	v_max3_f32 v0, v0, v68, v69
	v_max3_f32 v245, v245, v88, v89
	v_max3_f32 v0, v0, v86, v87
	v_max3_f32 v0, v0, v70, v71
	s_waitcnt lgkmcnt(6)
	v_mfma_f32_32x32x16_bf16 v[34:49], v[246:249], v[158:161], v[34:49]
	ds_read_b64_tr_b16 v[246:247], v234 offset:54272
	ds_read_b64_tr_b16 v[248:249], v234 offset:56320
	v_max3_f32 v245, v245, v72, v73
	v_max3_f32 v0, v0, v90, v91
	v_max3_f32 v245, v245, v92, v93
	v_max3_f32 v0, v0, v74, v75
	v_max3_f32 v245, v245, v76, v77
	v_max3_f32 v0, v0, v94, v95
	s_waitcnt lgkmcnt(6)
	v_mfma_f32_32x32x16_bf16 v[2:17], v[250:253], v[158:161], v[2:17]
	ds_read_b64_tr_b16 v[250:251], v234 offset:54784
	ds_read_b64_tr_b16 v[252:253], v234 offset:56832
	v_max3_f32 v245, v245, v96, v97
	v_max3_f32 v0, v0, v78, v79
	v_max3_f32 v245, v245, v80, v81
	v_max3_f32 v0, v0, v245, v245
	v_mov_b32_e32 v235, v0
	s_waitcnt lgkmcnt(6)
; __device__ __forceinline__ unsigned cvtpk(float lo, float hi) { unsigned r; asm volatile("v_cvt_pk_bf16_f32 %0, %1, %2" : "=v"(r) : "v"(lo), "v"(hi)); return r; }
; #define MLA_PVM(i) do { if ((i) & 1) { MLA_LD((i) + 1, vl0, vh0); MLA_MM(i, vl1, vh1); } else { MLA_LD((i) + 1, vl1, vh1); MLA_MM(i, vl0, vh0); } } while (0)
; #define MLA_F() __builtin_amdgcn_sched_barrier(0)
; __device__ __forceinline__ float attn_mla_lag(ALAS unsigned char* lds, const Args& A, int q0, f32x16 (&o)[4]) {
;     ...
;             { auto rr = __builtin_amdgcn_permlane32_swap(__float_as_uint(mx), __float_as_uint(mx), false, false); mx = __builtin_fmaxf(__uint_as_float(rr[0]), __uint_as_float(rr[1])); }
;             const float mnew = __builtin_fmaxf(mrun, mx);
;             alpha = __builtin_amdgcn_exp2f((mrun - mnew) * A.c1);
;             mrun = mnew;
;             const float nm = -mrun * A.c1;
;             f32x2 acc = {0.f, 0.f};
;             MLA_F();
;             MLA_PVM(4); MLA_EXPS(0); MLA_F();
;             MLA_PVM(5); MLA_EXPS(2); MLA_F();
;             MLA_PVM(6); MLA_EXPS(4); MLA_F();
;             MLA_PVM(7); MLA_EXPS(6); MLA_F();
;             MLA_PVM(8); MLA_EXPS(8); MLA_F();
;             MLA_PVM(9); MLA_EXPS(10); MLA_F();
;             MLA_PVM(10); MLA_EXPS(12); MLA_F();
;             MLA_PVM(11); MLA_EXPS(14); MLA_F();
;             MLA_PVM(12); lrun = __builtin_fmaf(lrun, alpha, acc.x + acc.y);
;             { u32x4 w; w.x = cvtpk(s0[0], s0[1]); w.y = cvtpk(s0[2], s0[3]); w.z = cvtpk(s0[4], s0[5]); w.w = cvtpk(s0[6], s0[7]); pa[0] = __builtin_bit_cast(bf16x8, w); } MLA_F();
;             MLA_PVM(13); { u32x4 w; w.x = cvtpk(s0[8], s0[9]); w.y = cvtpk(s0[10], s0[11]); w.z = cvtpk(s0[12], s0[13]); w.w = cvtpk(s0[14], s0[15]); pa[1] = __builtin_bit_cast(bf16x8, w); } MLA_F();
;             MLA_PVM(14); { u32x4 w; w.x = cvtpk(s1[0], s1[1]); w.y = cvtpk(s1[2], s1[3]); w.z = cvtpk(s1[4], s1[5]); w.w = cvtpk(s1[6], s1[7]); pa[2] = __builtin_bit_cast(bf16x8, w); } MLA_F();
;             MLA_PVM(15); MLA_F();
;             { u32x4 w; w.x = cvtpk(s1[8], s1[9]); w.y = cvtpk(s1[10], s1[11]); w.z = cvtpk(s1[12], s1[13]); w.w = cvtpk(s1[14], s1[15]); pa[3] = __builtin_bit_cast(bf16x8, w); }
	v_mfma_f32_32x32x16_bf16 v[18:33], v[224:227], v[154:157], v[18:33]
	ds_read_b64_tr_b16 v[224:225], v234 offset:57344
	ds_read_b64_tr_b16 v[226:227], v234 offset:59392
	v_permlane32_swap_b32_e32 v0, v235
	v_max3_f32 v245, v244, v0, v235
	v_sub_f32_e32 v0, v244, v245
	v_mul_f32_e32 v0, 0x3dd53b94, v0
	v_exp_f32_e32 v0, v0
	v_mul_f32_e32 v244, 0xbdd53b94, v245
	s_waitcnt lgkmcnt(6)
	v_mfma_f32_32x32x16_bf16 v[50:65], v[228:231], v[154:157], v[50:65]
	ds_read_b64_tr_b16 v[228:229], v234 offset:57856
	ds_read_b64_tr_b16 v[230:231], v234 offset:59904
	v_fma_f32 v82, v82, s76, v244
	v_fma_f32 v83, v83, s76, v244
	v_fma_f32 v239, v66, s76, v244
	v_fma_f32 v241, v67, s76, v244
	v_exp_f32_e32 v66, v82
	v_exp_f32_e32 v67, v83
	v_exp_f32_e32 v82, v239
	v_exp_f32_e32 v83, v241
	s_waitcnt lgkmcnt(6)
	v_mfma_f32_32x32x16_bf16 v[34:49], v[246:249], v[154:157], v[34:49]
	ds_read_b64_tr_b16 v[246:247], v234 offset:58368
	ds_read_b64_tr_b16 v[248:249], v234 offset:60416
	v_fma_f32 v84, v84, s76, v244
	v_fma_f32 v85, v85, s76, v244
	v_add_f32_e32 v236, 0, v66
	v_add_f32_e32 v237, 0, v67
	v_fma_f32 v239, v68, s76, v244
	v_fma_f32 v241, v69, s76, v244
	v_add_f32_e32 v236, v82, v236
	v_add_f32_e32 v237, v83, v237
	v_exp_f32_e32 v68, v84
	v_exp_f32_e32 v69, v85
	v_exp_f32_e32 v84, v239
	v_exp_f32_e32 v85, v241
	s_waitcnt lgkmcnt(6)
	v_mfma_f32_32x32x16_bf16 v[2:17], v[250:253], v[154:157], v[2:17]
	ds_read_b64_tr_b16 v[250:251], v234 offset:58880
	ds_read_b64_tr_b16 v[252:253], v234 offset:60928
	v_fma_f32 v86, v86, s76, v244
	v_fma_f32 v87, v87, s76, v244
	v_add_f32_e32 v236, v68, v236
	v_add_f32_e32 v237, v69, v237
	v_fma_f32 v239, v70, s76, v244
	v_fma_f32 v241, v71, s76, v244
	v_add_f32_e32 v236, v84, v236
	v_add_f32_e32 v237, v85, v237
	v_exp_f32_e32 v70, v86
	v_exp_f32_e32 v71, v87
	v_exp_f32_e32 v86, v239
	v_exp_f32_e32 v87, v241
	s_waitcnt lgkmcnt(6)
	v_mfma_f32_32x32x16_bf16 v[18:33], v[224:227], v[150:153], v[18:33]
	ds_read_b64_tr_b16 v[224:225], v234 offset:61440
	ds_read_b64_tr_b16 v[226:227], v234 offset:63488
	v_fma_f32 v88, v88, s76, v244
	v_fma_f32 v89, v89, s76, v244
	v_add_f32_e32 v236, v70, v236
	v_add_f32_e32 v237, v71, v237
	v_fma_f32 v239, v72, s76, v244
	v_fma_f32 v241, v73, s76, v244
	v_add_f32_e32 v236, v86, v236
	v_add_f32_e32 v237, v87, v237
	v_exp_f32_e32 v72, v88
	v_exp_f32_e32 v73, v89
	v_exp_f32_e32 v88, v239
	v_exp_f32_e32 v89, v241
	s_waitcnt lgkmcnt(6)
	v_mfma_f32_32x32x16_bf16 v[50:65], v[228:231], v[150:153], v[50:65]
	ds_read_b64_tr_b16 v[228:229], v234 offset:61952
	ds_read_b64_tr_b16 v[230:231], v234 offset:64000
	v_fma_f32 v90, v90, s76, v244
	v_fma_f32 v91, v91, s76, v244
	v_add_f32_e32 v236, v72, v236
	v_add_f32_e32 v237, v73, v237
	v_fma_f32 v239, v74, s76, v244
	v_fma_f32 v241, v75, s76, v244
	v_add_f32_e32 v236, v88, v236
	v_add_f32_e32 v237, v89, v237
	v_exp_f32_e32 v74, v90
	v_exp_f32_e32 v75, v91
	v_exp_f32_e32 v90, v239
	v_exp_f32_e32 v91, v241
	s_waitcnt lgkmcnt(6)
	v_mfma_f32_32x32x16_bf16 v[34:49], v[246:249], v[150:153], v[34:49]
	ds_read_b64_tr_b16 v[246:247], v234 offset:62464
	ds_read_b64_tr_b16 v[248:249], v234 offset:64512
	v_fma_f32 v92, v92, s76, v244
	v_fma_f32 v93, v93, s76, v244
	v_add_f32_e32 v236, v74, v236
	v_add_f32_e32 v237, v75, v237
	v_fma_f32 v239, v76, s76, v244
	v_fma_f32 v241, v77, s76, v244
	v_add_f32_e32 v236, v90, v236
	v_add_f32_e32 v237, v91, v237
	v_exp_f32_e32 v76, v92
	v_exp_f32_e32 v77, v93
	v_exp_f32_e32 v92, v239
	v_exp_f32_e32 v93, v241
	s_waitcnt lgkmcnt(6)
	v_mfma_f32_32x32x16_bf16 v[2:17], v[250:253], v[150:153], v[2:17]
	ds_read_b64_tr_b16 v[250:251], v234 offset:62976
	ds_read_b64_tr_b16 v[252:253], v234 offset:65024
	v_fma_f32 v94, v94, s76, v244
	v_fma_f32 v95, v95, s76, v244
	v_add_f32_e32 v236, v76, v236
	v_add_f32_e32 v237, v77, v237
	v_fma_f32 v239, v78, s76, v244
	v_fma_f32 v241, v79, s76, v244
	v_add_f32_e32 v236, v92, v236
	v_add_f32_e32 v237, v93, v237
	v_exp_f32_e32 v78, v94
	v_exp_f32_e32 v79, v95
	v_exp_f32_e32 v94, v239
	v_exp_f32_e32 v95, v241
	s_waitcnt lgkmcnt(6)
	v_mfma_f32_32x32x16_bf16 v[18:33], v[224:227], v[146:149], v[18:33]
	v_fma_f32 v96, v96, s76, v244
	v_fma_f32 v97, v97, s76, v244
	v_add_f32_e32 v236, v78, v236
	v_add_f32_e32 v237, v79, v237
	v_fma_f32 v239, v80, s76, v244
	v_fma_f32 v241, v81, s76, v244
	v_add_f32_e32 v236, v94, v236
	v_add_f32_e32 v237, v95, v237
	v_exp_f32_e32 v80, v96
	v_exp_f32_e32 v81, v97
	v_exp_f32_e32 v96, v239
	v_exp_f32_e32 v97, v241
	s_waitcnt lgkmcnt(4)
	v_mfma_f32_32x32x16_bf16 v[50:65], v[228:231], v[146:149], v[50:65]
	v_add_f32_e32 v236, v80, v236
	v_add_f32_e32 v237, v81, v237
	v_cvt_pk_bf16_f32 v158, v66, v67
	v_cvt_pk_bf16_f32 v159, v68, v69
	v_add_f32_e32 v236, v96, v236
	v_add_f32_e32 v237, v97, v237
	v_cvt_pk_bf16_f32 v160, v70, v71
	v_cvt_pk_bf16_f32 v161, v72, v73
	s_waitcnt lgkmcnt(2)
	v_mfma_f32_32x32x16_bf16 v[34:49], v[246:249], v[146:149], v[34:49]
	v_cvt_pk_bf16_f32 v154, v74, v75
	v_cvt_pk_bf16_f32 v155, v76, v77
	v_cvt_pk_bf16_f32 v156, v78, v79
	v_cvt_pk_bf16_f32 v157, v80, v81
	v_cvt_pk_bf16_f32 v150, v82, v83
	v_cvt_pk_bf16_f32 v151, v84, v85
	v_cvt_pk_bf16_f32 v152, v86, v87
	v_cvt_pk_bf16_f32 v153, v88, v89
	s_waitcnt lgkmcnt(0)
	v_mfma_f32_32x32x16_bf16 v[2:17], v[250:253], v[146:149], v[2:17]
	v_cvt_pk_bf16_f32 v146, v90, v91
	v_cvt_pk_bf16_f32 v147, v92, v93
	v_cvt_pk_bf16_f32 v148, v94, v95
	v_cvt_pk_bf16_f32 v149, v96, v97
	v_add_f32_e32 v246, v236, v237
	s_addk_i32 s5, 0x4000
	v_lshl_add_u64 v[216:217], v[216:217], 0, s[70:71]
	v_fmac_f32_e32 v246, v243, v0
	v_lshl_add_u64 v[214:215], v[214:215], 0, s[80:81]
	v_lshl_add_u64 v[212:213], v[212:213], 0, s[70:71]
	v_cmp_neq_f32_e32 vcc, 1.0, v0
	s_cbranch_vccz .Lmla_norescale
; __device__ __forceinline__ float attn_mla_lag(ALAS unsigned char* lds, const Args& A, int q0, f32x16 (&o)[4]) {
;     ...
;         if (__any(alpha != 1.0f)) {
; #pragma unroll
;             for (int db = 0; db < NDB; ++db)
; #pragma unroll
;                 for (int r = 0; r < 16; ++r) o[db][r] *= alpha;
;         }
	v_pk_mul_f32 v[32:33], v[0:1], v[32:33] op_sel_hi:[0,1]
	v_pk_mul_f32 v[30:31], v[0:1], v[30:31] op_sel_hi:[0,1]
	v_pk_mul_f32 v[28:29], v[0:1], v[28:29] op_sel_hi:[0,1]
	v_pk_mul_f32 v[26:27], v[0:1], v[26:27] op_sel_hi:[0,1]
	v_pk_mul_f32 v[24:25], v[0:1], v[24:25] op_sel_hi:[0,1]
	v_pk_mul_f32 v[22:23], v[0:1], v[22:23] op_sel_hi:[0,1]
	v_pk_mul_f32 v[20:21], v[0:1], v[20:21] op_sel_hi:[0,1]
	v_pk_mul_f32 v[18:19], v[0:1], v[18:19] op_sel_hi:[0,1]
	v_pk_mul_f32 v[64:65], v[0:1], v[64:65] op_sel_hi:[0,1]
	v_pk_mul_f32 v[62:63], v[0:1], v[62:63] op_sel_hi:[0,1]
	v_pk_mul_f32 v[60:61], v[0:1], v[60:61] op_sel_hi:[0,1]
	v_pk_mul_f32 v[58:59], v[0:1], v[58:59] op_sel_hi:[0,1]
	v_pk_mul_f32 v[56:57], v[0:1], v[56:57] op_sel_hi:[0,1]
	v_pk_mul_f32 v[54:55], v[0:1], v[54:55] op_sel_hi:[0,1]
	v_pk_mul_f32 v[52:53], v[0:1], v[52:53] op_sel_hi:[0,1]
	v_pk_mul_f32 v[50:51], v[0:1], v[50:51] op_sel_hi:[0,1]
	v_pk_mul_f32 v[48:49], v[0:1], v[48:49] op_sel_hi:[0,1]
	v_pk_mul_f32 v[46:47], v[0:1], v[46:47] op_sel_hi:[0,1]
	v_pk_mul_f32 v[44:45], v[0:1], v[44:45] op_sel_hi:[0,1]
	v_pk_mul_f32 v[42:43], v[0:1], v[42:43] op_sel_hi:[0,1]
	v_pk_mul_f32 v[40:41], v[0:1], v[40:41] op_sel_hi:[0,1]
	v_pk_mul_f32 v[38:39], v[0:1], v[38:39] op_sel_hi:[0,1]
	v_pk_mul_f32 v[36:37], v[0:1], v[36:37] op_sel_hi:[0,1]
	v_pk_mul_f32 v[34:35], v[0:1], v[34:35] op_sel_hi:[0,1]
	v_pk_mul_f32 v[16:17], v[0:1], v[16:17] op_sel_hi:[0,1]
	v_pk_mul_f32 v[14:15], v[0:1], v[14:15] op_sel_hi:[0,1]
	v_pk_mul_f32 v[12:13], v[0:1], v[12:13] op_sel_hi:[0,1]
	v_pk_mul_f32 v[10:11], v[0:1], v[10:11] op_sel_hi:[0,1]
	v_pk_mul_f32 v[8:9], v[0:1], v[8:9] op_sel_hi:[0,1]
	v_pk_mul_f32 v[6:7], v[0:1], v[6:7] op_sel_hi:[0,1]
	v_pk_mul_f32 v[4:5], v[0:1], v[4:5] op_sel_hi:[0,1]
	v_pk_mul_f32 v[2:3], v[0:1], v[2:3] op_sel_hi:[0,1]
